# adds: gelu epilogue x/(1+e) computed as x*rcp(1+e) in f32 (result rounded to bf16 as before) instead of the IEEE division expansion
# baseline (speedup 1.0000x reference)
.LBB0_129:
	s_cmp_lt_i32 s12, 64
	s_cselect_b64 s[8:9], -1, 0
	s_lshl_b32 s11, s12, 8
	v_readlane_b32 s12, v249, 55
	s_add_i32 s14, s11, s12
	s_cmp_gt_i32 s10, 11
	v_or_b32_e32 v170, s14, v148
	s_cselect_b64 s[12:13], -1, 0
	s_cmp_gt_u32 s10, 15
	s_cselect_b64 s[30:31], -1, 0
	s_cmp_gt_u32 s10, 23
	v_add_u32_e32 v180, 0xffffc000, v170
	s_cselect_b64 s[18:19], -1, 0
	s_lshl_b32 s42, s10, 8
	s_add_i32 s17, s10, -12
	v_ashrrev_i32_e32 v130, 4, v180
	s_add_i32 s56, s42, 0xffffe800
	s_lshl_b32 s40, s17, 8
	v_add_u32_e32 v130, s17, v130
	s_cmp_gt_i32 s10, 7
	v_mad_i64_i32 v[172:173], s[10:11], v130, s71, 0
	s_cselect_b64 s[38:39], -1, 0
	s_ashr_i32 s10, s14, 10
	s_and_b32 s10, s10, -4
	s_add_i32 s10, s10, s17
	s_ashr_i32 s11, s10, 31
	s_mov_b32 s43, s57
	s_mov_b32 s41, s57
	s_lshl_b64 s[28:29], s[10:11], 21
	s_mov_b64 s[10:11], -1
	s_and_b64 vcc, exec, s[12:13]
	s_cbranch_vccz .LBB0_139
	s_and_b64 vcc, exec, s[30:31]
	s_cbranch_vccz .LBB0_136
	v_ashrrev_i32_e32 v171, 31, v170
	v_lshlrev_b64 v[130:131], 12, v[170:171]
	s_and_b64 vcc, exec, s[18:19]
	s_cbranch_vccz .LBB0_133
	v_mul_f32_e32 v134, 0x3d372713, v126
	v_mul_f32_e32 v134, v126, v134
	v_fma_f32 v134, v126, v134, v126
	v_mul_f32_e32 v134, 0xbfcc422a, v134
	v_mul_f32_e32 v134, 0x3fb8aa3b, v134
	v_exp_f32_e32 v134, v134
	v_lshl_add_u64 v[132:133], s[48:49], 0, v[130:131]
	v_lshl_add_u64 v[132:133], s[56:57], 1, v[132:133]
	v_lshlrev_b32_e32 v146, 1, v158
	v_add_f32_e32 v134, 1.0, v134
	v_lshl_add_u64 v[132:133], v[132:133], 0, v[146:147]
	v_rcp_f32_e32 v135, v134
	s_nop 0
	v_mul_f32_e32 v134, v126, v135
	v_mul_f32_e32 v135, 0x3d372713, v122
	v_mul_f32_e32 v135, v122, v135
	v_fma_f32 v135, v122, v135, v122
	v_mul_f32_e32 v135, 0xbfcc422a, v135
	v_mul_f32_e32 v135, 0x3fb8aa3b, v135
	v_exp_f32_e32 v135, v135
	s_nop 0
	v_add_f32_e32 v135, 1.0, v135
	s_nop 0
	v_rcp_f32_e32 v136, v135
	s_nop 0
	v_mul_f32_e32 v136, v122, v136
	v_mul_f32_e32 v135, 0x3d372713, v127
	v_mul_f32_e32 v135, v127, v135
	v_fma_f32 v135, v127, v135, v127
	v_mul_f32_e32 v135, 0xbfcc422a, v135
	v_mul_f32_e32 v135, 0x3fb8aa3b, v135
	v_exp_f32_e32 v135, v135
	s_nop 0
	v_add_f32_e32 v135, 1.0, v135
	s_nop 0
	v_rcp_f32_e32 v137, v135
	s_nop 0
	v_mul_f32_e32 v135, v127, v137
	v_mul_f32_e32 v137, 0x3d372713, v123
	v_mul_f32_e32 v137, v123, v137
	v_fma_f32 v137, v123, v137, v123
	v_mul_f32_e32 v137, 0xbfcc422a, v137
	v_mul_f32_e32 v137, 0x3fb8aa3b, v137
	v_exp_f32_e32 v137, v137
	v_cvt_pk_bf16_f32 v134, v134, v135
	s_nop 0
	v_add_f32_e32 v137, 1.0, v137
	s_nop 0
	v_rcp_f32_e32 v146, v137
	s_nop 0
	v_mul_f32_e32 v137, v123, v146
	v_mul_f32_e32 v146, 0x3d372713, v128
	v_mul_f32_e32 v146, v128, v146
	v_fma_f32 v146, v128, v146, v128
	v_mul_f32_e32 v146, 0xbfcc422a, v146
	v_mul_f32_e32 v146, 0x3fb8aa3b, v146
	v_exp_f32_e32 v146, v146
	s_nop 0
	v_add_f32_e32 v146, 1.0, v146
	s_nop 0
	v_rcp_f32_e32 v171, v146
	s_nop 0
	v_mul_f32_e32 v146, v128, v171
	v_mul_f32_e32 v171, 0x3d372713, v124
	v_mul_f32_e32 v171, v124, v171
	v_fma_f32 v171, v124, v171, v124
	v_mul_f32_e32 v171, 0xbfcc422a, v171
	v_mul_f32_e32 v171, 0x3fb8aa3b, v171
	v_exp_f32_e32 v171, v171
	s_nop 0
	v_add_f32_e32 v171, 1.0, v171
	s_nop 0
	v_rcp_f32_e32 v174, v171
	s_nop 0
	v_mul_f32_e32 v171, v124, v174
	v_mul_f32_e32 v174, 0x3d372713, v129
	v_mul_f32_e32 v174, v129, v174
	v_fma_f32 v174, v129, v174, v129
	v_mul_f32_e32 v174, 0xbfcc422a, v174
	v_mul_f32_e32 v174, 0x3fb8aa3b, v174
	v_exp_f32_e32 v174, v174
	s_nop 0
	v_add_f32_e32 v174, 1.0, v174
	s_nop 0
	v_rcp_f32_e32 v175, v174
	s_nop 0
	v_mul_f32_e32 v174, v129, v175
	v_mul_f32_e32 v175, 0x3d372713, v125
	v_mul_f32_e32 v175, v125, v175
	v_fma_f32 v175, v125, v175, v125
	v_mul_f32_e32 v175, 0xbfcc422a, v175
	v_mul_f32_e32 v175, 0x3fb8aa3b, v175
	v_exp_f32_e32 v175, v175
	v_cvt_pk_bf16_f32 v135, v146, v174
	v_cvt_pk_bf16_f32 v136, v136, v137
	s_nop 0
	v_add_f32_e32 v175, 1.0, v175
	s_nop 0
	v_rcp_f32_e32 v181, v175
	s_nop 0
	v_mul_f32_e32 v175, v125, v181
	v_cvt_pk_bf16_f32 v137, v171, v175
	global_store_dwordx4 v[132:133], v[134:137], off
	s_nop 1
	v_mul_f32_e32 v134, 0x3d372713, v118
	v_mul_f32_e32 v134, v118, v134
	v_fma_f32 v134, v118, v134, v118
	v_mul_f32_e32 v134, 0xbfcc422a, v134
	v_mul_f32_e32 v134, 0x3fb8aa3b, v134
	v_exp_f32_e32 v134, v134
	s_nop 0
	v_add_f32_e32 v134, 1.0, v134
	s_nop 0
	v_rcp_f32_e32 v135, v134
	s_nop 0
	v_mul_f32_e32 v134, v118, v135
	v_mul_f32_e32 v135, 0x3d372713, v114
	v_mul_f32_e32 v135, v114, v135
	v_fma_f32 v135, v114, v135, v114
	v_mul_f32_e32 v135, 0xbfcc422a, v135
	v_mul_f32_e32 v135, 0x3fb8aa3b, v135
	v_exp_f32_e32 v135, v135
	s_nop 0
	v_add_f32_e32 v135, 1.0, v135
	s_nop 0
	v_rcp_f32_e32 v136, v135
	s_nop 0
	v_mul_f32_e32 v136, v114, v136
	v_mul_f32_e32 v135, 0x3d372713, v119
	v_mul_f32_e32 v135, v119, v135
	v_fma_f32 v135, v119, v135, v119
	v_mul_f32_e32 v135, 0xbfcc422a, v135
	v_mul_f32_e32 v135, 0x3fb8aa3b, v135
	v_exp_f32_e32 v135, v135
	s_nop 0
	v_add_f32_e32 v135, 1.0, v135
	s_nop 0
	v_rcp_f32_e32 v137, v135
	s_nop 0
	v_mul_f32_e32 v135, v119, v137
	v_mul_f32_e32 v137, 0x3d372713, v115
	v_mul_f32_e32 v137, v115, v137
	v_fma_f32 v137, v115, v137, v115
	v_mul_f32_e32 v137, 0xbfcc422a, v137
	v_mul_f32_e32 v137, 0x3fb8aa3b, v137
	v_exp_f32_e32 v137, v137
	v_cvt_pk_bf16_f32 v134, v134, v135
	s_nop 0
	v_add_f32_e32 v137, 1.0, v137
	s_nop 0
	v_rcp_f32_e32 v146, v137
	s_nop 0
	v_mul_f32_e32 v137, v115, v146
	v_mul_f32_e32 v146, 0x3d372713, v120
	v_mul_f32_e32 v146, v120, v146
	v_fma_f32 v146, v120, v146, v120
	v_mul_f32_e32 v146, 0xbfcc422a, v146
	v_mul_f32_e32 v146, 0x3fb8aa3b, v146
	v_exp_f32_e32 v146, v146
	s_nop 0
	v_add_f32_e32 v146, 1.0, v146
	s_nop 0
	v_rcp_f32_e32 v171, v146
	s_nop 0
	v_mul_f32_e32 v146, v120, v171
	v_mul_f32_e32 v171, 0x3d372713, v116
	v_mul_f32_e32 v171, v116, v171
	v_fma_f32 v171, v116, v171, v116
	v_mul_f32_e32 v171, 0xbfcc422a, v171
	v_mul_f32_e32 v171, 0x3fb8aa3b, v171
	v_exp_f32_e32 v171, v171
	s_nop 0
	v_add_f32_e32 v171, 1.0, v171
	s_nop 0
	v_rcp_f32_e32 v174, v171
	s_nop 0
	v_mul_f32_e32 v171, v116, v174
	v_mul_f32_e32 v174, 0x3d372713, v121
	v_mul_f32_e32 v174, v121, v174
	v_fma_f32 v174, v121, v174, v121
	v_mul_f32_e32 v174, 0xbfcc422a, v174
	v_mul_f32_e32 v174, 0x3fb8aa3b, v174
	v_exp_f32_e32 v174, v174
	s_nop 0
	v_add_f32_e32 v174, 1.0, v174
	s_nop 0
	v_rcp_f32_e32 v175, v174
	s_nop 0
	v_mul_f32_e32 v174, v121, v175
	v_mul_f32_e32 v175, 0x3d372713, v117
	v_mul_f32_e32 v175, v117, v175
	v_fma_f32 v175, v117, v175, v117
	v_mul_f32_e32 v175, 0xbfcc422a, v175
	v_mul_f32_e32 v175, 0x3fb8aa3b, v175
	v_exp_f32_e32 v175, v175
	v_cvt_pk_bf16_f32 v135, v146, v174
	v_cvt_pk_bf16_f32 v136, v136, v137
	s_nop 0
	v_add_f32_e32 v175, 1.0, v175
	s_mov_b64 s[10:11], 0
	v_rcp_f32_e32 v181, v175
	s_nop 0
	v_mul_f32_e32 v175, v117, v181
	v_cvt_pk_bf16_f32 v137, v171, v175
	global_store_dwordx4 v[132:133], v[134:137], off offset:256

.LBB0_146:
	s_nop 1
	v_cndmask_b32_e64 v114, 0, 1, s[12:13]
	v_cmp_ne_u32_e64 s[14:15], 1, v114
	v_cndmask_b32_e64 v114, 0, 1, s[30:31]
	v_or_b32_e32 v122, 16, v170
	s_mov_b64 s[84:85], -1
	s_andn2_b64 vcc, exec, s[12:13]
	v_cmp_ne_u32_e64 s[12:13], 1, v114
	s_cbranch_vccnz .LBB0_156
	s_and_b64 vcc, exec, s[12:13]
	s_mov_b64 s[30:31], -1
	s_cbranch_vccnz .LBB0_153
	v_ashrrev_i32_e32 v123, 31, v122
	v_lshlrev_b64 v[114:115], 12, v[122:123]
	s_andn2_b64 vcc, exec, s[18:19]
	s_cbranch_vccnz .LBB0_150
	v_mul_f32_e32 v118, 0x3d372713, v110
	v_mul_f32_e32 v118, v110, v118
	v_fma_f32 v118, v110, v118, v110
	v_mul_f32_e32 v118, 0xbfcc422a, v118
	v_mul_f32_e32 v118, 0x3fb8aa3b, v118
	v_exp_f32_e32 v118, v118
	v_lshl_add_u64 v[116:117], s[48:49], 0, v[114:115]
	v_lshl_add_u64 v[116:117], s[56:57], 1, v[116:117]
	v_lshlrev_b32_e32 v146, 1, v158
	v_add_f32_e32 v118, 1.0, v118
	v_lshl_add_u64 v[116:117], v[116:117], 0, v[146:147]
	v_rcp_f32_e32 v119, v118
	s_nop 0
	v_mul_f32_e32 v118, v110, v119
	v_mul_f32_e32 v119, 0x3d372713, v106
	v_mul_f32_e32 v119, v106, v119
	v_fma_f32 v119, v106, v119, v106
	v_mul_f32_e32 v119, 0xbfcc422a, v119
	v_mul_f32_e32 v119, 0x3fb8aa3b, v119
	v_exp_f32_e32 v119, v119
	s_nop 0
	v_add_f32_e32 v119, 1.0, v119
	s_nop 0
	v_rcp_f32_e32 v120, v119
	s_nop 0
	v_mul_f32_e32 v120, v106, v120
	v_mul_f32_e32 v119, 0x3d372713, v111
	v_mul_f32_e32 v119, v111, v119
	v_fma_f32 v119, v111, v119, v111
	v_mul_f32_e32 v119, 0xbfcc422a, v119
	v_mul_f32_e32 v119, 0x3fb8aa3b, v119
	v_exp_f32_e32 v119, v119
	s_nop 0
	v_add_f32_e32 v119, 1.0, v119
	s_nop 0
	v_rcp_f32_e32 v121, v119
	s_nop 0
	v_mul_f32_e32 v119, v111, v121
	v_mul_f32_e32 v121, 0x3d372713, v107
	v_mul_f32_e32 v121, v107, v121
	v_fma_f32 v121, v107, v121, v107
	v_mul_f32_e32 v121, 0xbfcc422a, v121
	v_mul_f32_e32 v121, 0x3fb8aa3b, v121
	v_exp_f32_e32 v121, v121
	v_cvt_pk_bf16_f32 v118, v118, v119
	s_nop 0
	v_add_f32_e32 v121, 1.0, v121
	s_nop 0
	v_rcp_f32_e32 v123, v121
	s_nop 0
	v_mul_f32_e32 v121, v107, v123
	v_mul_f32_e32 v123, 0x3d372713, v112
	v_mul_f32_e32 v123, v112, v123
	v_fma_f32 v123, v112, v123, v112
	v_mul_f32_e32 v123, 0xbfcc422a, v123
	v_mul_f32_e32 v123, 0x3fb8aa3b, v123
	v_exp_f32_e32 v123, v123
	s_nop 0
	v_add_f32_e32 v123, 1.0, v123
	s_nop 0
	v_rcp_f32_e32 v124, v123
	s_nop 0
	v_mul_f32_e32 v123, v112, v124
	v_mul_f32_e32 v124, 0x3d372713, v108
	v_mul_f32_e32 v124, v108, v124
	v_fma_f32 v124, v108, v124, v108
	v_mul_f32_e32 v124, 0xbfcc422a, v124
	v_mul_f32_e32 v124, 0x3fb8aa3b, v124
	v_exp_f32_e32 v124, v124
	s_nop 0
	v_add_f32_e32 v124, 1.0, v124
	s_nop 0
	v_rcp_f32_e32 v125, v124
	s_nop 0
	v_mul_f32_e32 v124, v108, v125
	v_mul_f32_e32 v125, 0x3d372713, v113
	v_mul_f32_e32 v125, v113, v125
	v_fma_f32 v125, v113, v125, v113
	v_mul_f32_e32 v125, 0xbfcc422a, v125
	v_mul_f32_e32 v125, 0x3fb8aa3b, v125
	v_exp_f32_e32 v125, v125
	s_nop 0
	v_add_f32_e32 v125, 1.0, v125
	s_nop 0
	v_rcp_f32_e32 v126, v125
	s_nop 0
	v_mul_f32_e32 v125, v113, v126
	v_mul_f32_e32 v126, 0x3d372713, v109
	v_mul_f32_e32 v126, v109, v126
	v_fma_f32 v126, v109, v126, v109
	v_mul_f32_e32 v126, 0xbfcc422a, v126
	v_mul_f32_e32 v126, 0x3fb8aa3b, v126
	v_exp_f32_e32 v126, v126
	v_cvt_pk_bf16_f32 v119, v123, v125
	v_cvt_pk_bf16_f32 v120, v120, v121
	s_nop 0
	v_add_f32_e32 v126, 1.0, v126
	s_nop 0
	v_rcp_f32_e32 v127, v126
	s_nop 0
	v_mul_f32_e32 v126, v109, v127
	v_cvt_pk_bf16_f32 v121, v124, v126
	global_store_dwordx4 v[116:117], v[118:121], off
	s_nop 1
	v_mul_f32_e32 v118, 0x3d372713, v102
	v_mul_f32_e32 v118, v102, v118
	v_fma_f32 v118, v102, v118, v102
	v_mul_f32_e32 v118, 0xbfcc422a, v118
	v_mul_f32_e32 v118, 0x3fb8aa3b, v118
	v_exp_f32_e32 v118, v118
	s_nop 0
	v_add_f32_e32 v118, 1.0, v118
	s_nop 0
	v_rcp_f32_e32 v119, v118
	s_nop 0
	v_mul_f32_e32 v118, v102, v119
	v_mul_f32_e32 v119, 0x3d372713, v98
	v_mul_f32_e32 v119, v98, v119
	v_fma_f32 v119, v98, v119, v98
	v_mul_f32_e32 v119, 0xbfcc422a, v119
	v_mul_f32_e32 v119, 0x3fb8aa3b, v119
	v_exp_f32_e32 v119, v119
	s_nop 0
	v_add_f32_e32 v119, 1.0, v119
	s_nop 0
	v_rcp_f32_e32 v120, v119
	s_nop 0
	v_mul_f32_e32 v120, v98, v120
	v_mul_f32_e32 v119, 0x3d372713, v103
	v_mul_f32_e32 v119, v103, v119
	v_fma_f32 v119, v103, v119, v103
	v_mul_f32_e32 v119, 0xbfcc422a, v119
	v_mul_f32_e32 v119, 0x3fb8aa3b, v119
	v_exp_f32_e32 v119, v119
	s_nop 0
	v_add_f32_e32 v119, 1.0, v119
	s_nop 0
	v_rcp_f32_e32 v121, v119
	s_nop 0
	v_mul_f32_e32 v119, v103, v121
	v_mul_f32_e32 v121, 0x3d372713, v99
	v_mul_f32_e32 v121, v99, v121
	v_fma_f32 v121, v99, v121, v99
	v_mul_f32_e32 v121, 0xbfcc422a, v121
	v_mul_f32_e32 v121, 0x3fb8aa3b, v121
	v_exp_f32_e32 v121, v121
	v_cvt_pk_bf16_f32 v118, v118, v119
	s_nop 0
	v_add_f32_e32 v121, 1.0, v121
	s_nop 0
	v_rcp_f32_e32 v123, v121
	s_nop 0
	v_mul_f32_e32 v121, v99, v123
	v_mul_f32_e32 v123, 0x3d372713, v104
	v_mul_f32_e32 v123, v104, v123
	v_fma_f32 v123, v104, v123, v104
	v_mul_f32_e32 v123, 0xbfcc422a, v123
	v_mul_f32_e32 v123, 0x3fb8aa3b, v123
	v_exp_f32_e32 v123, v123
	s_nop 0
	v_add_f32_e32 v123, 1.0, v123
	s_nop 0
	v_rcp_f32_e32 v124, v123
	s_nop 0
	v_mul_f32_e32 v123, v104, v124
	v_mul_f32_e32 v124, 0x3d372713, v100
	v_mul_f32_e32 v124, v100, v124
	v_fma_f32 v124, v100, v124, v100
	v_mul_f32_e32 v124, 0xbfcc422a, v124
	v_mul_f32_e32 v124, 0x3fb8aa3b, v124
	v_exp_f32_e32 v124, v124
	s_nop 0
	v_add_f32_e32 v124, 1.0, v124
	s_nop 0
	v_rcp_f32_e32 v125, v124
	s_nop 0
	v_mul_f32_e32 v124, v100, v125
	v_mul_f32_e32 v125, 0x3d372713, v105
	v_mul_f32_e32 v125, v105, v125
	v_fma_f32 v125, v105, v125, v105
	v_mul_f32_e32 v125, 0xbfcc422a, v125
	v_mul_f32_e32 v125, 0x3fb8aa3b, v125
	v_exp_f32_e32 v125, v125
	s_nop 0
	v_add_f32_e32 v125, 1.0, v125
	s_nop 0
	v_rcp_f32_e32 v126, v125
	s_nop 0
	v_mul_f32_e32 v125, v105, v126
	v_mul_f32_e32 v126, 0x3d372713, v101
	v_mul_f32_e32 v126, v101, v126
	v_fma_f32 v126, v101, v126, v101
	v_mul_f32_e32 v126, 0xbfcc422a, v126
	v_mul_f32_e32 v126, 0x3fb8aa3b, v126
	v_exp_f32_e32 v126, v126
	v_cvt_pk_bf16_f32 v119, v123, v125
	v_cvt_pk_bf16_f32 v120, v120, v121
	s_nop 0
	v_add_f32_e32 v126, 1.0, v126
	s_mov_b64 s[30:31], 0
	v_rcp_f32_e32 v127, v126
	s_nop 0
	v_mul_f32_e32 v126, v101, v127
	v_cvt_pk_bf16_f32 v121, v124, v126
	global_store_dwordx4 v[116:117], v[118:121], off offset:256

.LBB0_163:
	v_or_b32_e32 v106, 32, v170
	s_and_b64 vcc, exec, s[14:15]
	s_mov_b64 s[30:31], -1
	s_cbranch_vccnz .LBB0_173
	s_and_b64 vcc, exec, s[12:13]
	s_cbranch_vccnz .LBB0_170
	v_ashrrev_i32_e32 v107, 31, v106
	v_lshlrev_b64 v[98:99], 12, v[106:107]
	s_andn2_b64 vcc, exec, s[18:19]
	s_cbranch_vccnz .LBB0_167
	v_mul_f32_e32 v102, 0x3d372713, v94
	v_mul_f32_e32 v102, v94, v102
	v_fma_f32 v102, v94, v102, v94
	v_mul_f32_e32 v102, 0xbfcc422a, v102
	v_mul_f32_e32 v102, 0x3fb8aa3b, v102
	v_exp_f32_e32 v102, v102
	v_lshl_add_u64 v[100:101], s[48:49], 0, v[98:99]
	v_lshl_add_u64 v[100:101], s[56:57], 1, v[100:101]
	v_lshlrev_b32_e32 v146, 1, v158
	v_add_f32_e32 v102, 1.0, v102
	v_lshl_add_u64 v[100:101], v[100:101], 0, v[146:147]
	v_rcp_f32_e32 v103, v102
	s_nop 0
	v_mul_f32_e32 v102, v94, v103
	v_mul_f32_e32 v103, 0x3d372713, v90
	v_mul_f32_e32 v103, v90, v103
	v_fma_f32 v103, v90, v103, v90
	v_mul_f32_e32 v103, 0xbfcc422a, v103
	v_mul_f32_e32 v103, 0x3fb8aa3b, v103
	v_exp_f32_e32 v103, v103
	s_nop 0
	v_add_f32_e32 v103, 1.0, v103
	s_nop 0
	v_rcp_f32_e32 v104, v103
	s_nop 0
	v_mul_f32_e32 v104, v90, v104
	v_mul_f32_e32 v103, 0x3d372713, v95
	v_mul_f32_e32 v103, v95, v103
	v_fma_f32 v103, v95, v103, v95
	v_mul_f32_e32 v103, 0xbfcc422a, v103
	v_mul_f32_e32 v103, 0x3fb8aa3b, v103
	v_exp_f32_e32 v103, v103
	s_nop 0
	v_add_f32_e32 v103, 1.0, v103
	s_nop 0
	v_rcp_f32_e32 v105, v103
	s_nop 0
	v_mul_f32_e32 v103, v95, v105
	v_mul_f32_e32 v105, 0x3d372713, v91
	v_mul_f32_e32 v105, v91, v105
	v_fma_f32 v105, v91, v105, v91
	v_mul_f32_e32 v105, 0xbfcc422a, v105
	v_mul_f32_e32 v105, 0x3fb8aa3b, v105
	v_exp_f32_e32 v105, v105
	v_cvt_pk_bf16_f32 v102, v102, v103
	s_nop 0
	v_add_f32_e32 v105, 1.0, v105
	s_nop 0
	v_rcp_f32_e32 v107, v105
	s_nop 0
	v_mul_f32_e32 v105, v91, v107
	v_mul_f32_e32 v107, 0x3d372713, v96
	v_mul_f32_e32 v107, v96, v107
	v_fma_f32 v107, v96, v107, v96
	v_mul_f32_e32 v107, 0xbfcc422a, v107
	v_mul_f32_e32 v107, 0x3fb8aa3b, v107
	v_exp_f32_e32 v107, v107
	s_nop 0
	v_add_f32_e32 v107, 1.0, v107
	s_nop 0
	v_rcp_f32_e32 v108, v107
	s_nop 0
	v_mul_f32_e32 v107, v96, v108
	v_mul_f32_e32 v108, 0x3d372713, v92
	v_mul_f32_e32 v108, v92, v108
	v_fma_f32 v108, v92, v108, v92
	v_mul_f32_e32 v108, 0xbfcc422a, v108
	v_mul_f32_e32 v108, 0x3fb8aa3b, v108
	v_exp_f32_e32 v108, v108
	s_nop 0
	v_add_f32_e32 v108, 1.0, v108
	s_nop 0
	v_rcp_f32_e32 v109, v108
	s_nop 0
	v_mul_f32_e32 v108, v92, v109
	v_mul_f32_e32 v109, 0x3d372713, v97
	v_mul_f32_e32 v109, v97, v109
	v_fma_f32 v109, v97, v109, v97
	v_mul_f32_e32 v109, 0xbfcc422a, v109
	v_mul_f32_e32 v109, 0x3fb8aa3b, v109
	v_exp_f32_e32 v109, v109
	s_nop 0
	v_add_f32_e32 v109, 1.0, v109
	s_nop 0
	v_rcp_f32_e32 v110, v109
	s_nop 0
	v_mul_f32_e32 v109, v97, v110
	v_mul_f32_e32 v110, 0x3d372713, v93
	v_mul_f32_e32 v110, v93, v110
	v_fma_f32 v110, v93, v110, v93
	v_mul_f32_e32 v110, 0xbfcc422a, v110
	v_mul_f32_e32 v110, 0x3fb8aa3b, v110
	v_exp_f32_e32 v110, v110
	v_cvt_pk_bf16_f32 v103, v107, v109
	v_cvt_pk_bf16_f32 v104, v104, v105
	s_nop 0
	v_add_f32_e32 v110, 1.0, v110
	s_nop 0
	v_rcp_f32_e32 v111, v110
	s_nop 0
	v_mul_f32_e32 v110, v93, v111
	v_cvt_pk_bf16_f32 v105, v108, v110
	global_store_dwordx4 v[100:101], v[102:105], off
	s_nop 1
	v_mul_f32_e32 v102, 0x3d372713, v86
	v_mul_f32_e32 v102, v86, v102
	v_fma_f32 v102, v86, v102, v86
	v_mul_f32_e32 v102, 0xbfcc422a, v102
	v_mul_f32_e32 v102, 0x3fb8aa3b, v102
	v_exp_f32_e32 v102, v102
	s_nop 0
	v_add_f32_e32 v102, 1.0, v102
	s_nop 0
	v_rcp_f32_e32 v103, v102
	s_nop 0
	v_mul_f32_e32 v102, v86, v103
	v_mul_f32_e32 v103, 0x3d372713, v82
	v_mul_f32_e32 v103, v82, v103
	v_fma_f32 v103, v82, v103, v82
	v_mul_f32_e32 v103, 0xbfcc422a, v103
	v_mul_f32_e32 v103, 0x3fb8aa3b, v103
	v_exp_f32_e32 v103, v103
	s_nop 0
	v_add_f32_e32 v103, 1.0, v103
	s_nop 0
	v_rcp_f32_e32 v104, v103
	s_nop 0
	v_mul_f32_e32 v104, v82, v104
	v_mul_f32_e32 v103, 0x3d372713, v87
	v_mul_f32_e32 v103, v87, v103
	v_fma_f32 v103, v87, v103, v87
	v_mul_f32_e32 v103, 0xbfcc422a, v103
	v_mul_f32_e32 v103, 0x3fb8aa3b, v103
	v_exp_f32_e32 v103, v103
	s_nop 0
	v_add_f32_e32 v103, 1.0, v103
	s_nop 0
	v_rcp_f32_e32 v105, v103
	s_nop 0
	v_mul_f32_e32 v103, v87, v105
	v_mul_f32_e32 v105, 0x3d372713, v83
	v_mul_f32_e32 v105, v83, v105
	v_fma_f32 v105, v83, v105, v83
	v_mul_f32_e32 v105, 0xbfcc422a, v105
	v_mul_f32_e32 v105, 0x3fb8aa3b, v105
	v_exp_f32_e32 v105, v105
	v_cvt_pk_bf16_f32 v102, v102, v103
	s_nop 0
	v_add_f32_e32 v105, 1.0, v105
	s_nop 0
	v_rcp_f32_e32 v107, v105
	s_nop 0
	v_mul_f32_e32 v105, v83, v107
	v_mul_f32_e32 v107, 0x3d372713, v88
	v_mul_f32_e32 v107, v88, v107
	v_fma_f32 v107, v88, v107, v88
	v_mul_f32_e32 v107, 0xbfcc422a, v107
	v_mul_f32_e32 v107, 0x3fb8aa3b, v107
	v_exp_f32_e32 v107, v107
	s_nop 0
	v_add_f32_e32 v107, 1.0, v107
	s_nop 0
	v_rcp_f32_e32 v108, v107
	s_nop 0
	v_mul_f32_e32 v107, v88, v108
	v_mul_f32_e32 v108, 0x3d372713, v84
	v_mul_f32_e32 v108, v84, v108
	v_fma_f32 v108, v84, v108, v84
	v_mul_f32_e32 v108, 0xbfcc422a, v108
	v_mul_f32_e32 v108, 0x3fb8aa3b, v108
	v_exp_f32_e32 v108, v108
	s_nop 0
	v_add_f32_e32 v108, 1.0, v108
	s_nop 0
	v_rcp_f32_e32 v109, v108
	s_nop 0
	v_mul_f32_e32 v108, v84, v109
	v_mul_f32_e32 v109, 0x3d372713, v89
	v_mul_f32_e32 v109, v89, v109
	v_fma_f32 v109, v89, v109, v89
	v_mul_f32_e32 v109, 0xbfcc422a, v109
	v_mul_f32_e32 v109, 0x3fb8aa3b, v109
	v_exp_f32_e32 v109, v109
	s_nop 0
	v_add_f32_e32 v109, 1.0, v109
	s_nop 0
	v_rcp_f32_e32 v110, v109
	s_nop 0
	v_mul_f32_e32 v109, v89, v110
	v_mul_f32_e32 v110, 0x3d372713, v85
	v_mul_f32_e32 v110, v85, v110
	v_fma_f32 v110, v85, v110, v85
	v_mul_f32_e32 v110, 0xbfcc422a, v110
	v_mul_f32_e32 v110, 0x3fb8aa3b, v110
	v_exp_f32_e32 v110, v110
	v_cvt_pk_bf16_f32 v103, v107, v109
	v_cvt_pk_bf16_f32 v104, v104, v105
	s_nop 0
	v_add_f32_e32 v110, 1.0, v110
	s_mov_b64 s[30:31], 0
	v_rcp_f32_e32 v111, v110
	s_nop 0
	v_mul_f32_e32 v110, v85, v111
	v_cvt_pk_bf16_f32 v105, v108, v110
	global_store_dwordx4 v[100:101], v[102:105], off offset:256

.LBB0_180:
	v_or_b32_e32 v90, 48, v170
	s_and_b64 vcc, exec, s[14:15]
	s_mov_b64 s[30:31], -1
	s_cbranch_vccnz .LBB0_190
	s_and_b64 vcc, exec, s[12:13]
	s_cbranch_vccnz .LBB0_187
	v_ashrrev_i32_e32 v91, 31, v90
	v_lshlrev_b64 v[82:83], 12, v[90:91]
	s_andn2_b64 vcc, exec, s[18:19]
	s_cbranch_vccnz .LBB0_184
	v_mul_f32_e32 v86, 0x3d372713, v78
	v_mul_f32_e32 v86, v78, v86
	v_fma_f32 v86, v78, v86, v78
	v_mul_f32_e32 v86, 0xbfcc422a, v86
	v_mul_f32_e32 v86, 0x3fb8aa3b, v86
	v_exp_f32_e32 v86, v86
	v_lshl_add_u64 v[84:85], s[48:49], 0, v[82:83]
	v_lshl_add_u64 v[84:85], s[56:57], 1, v[84:85]
	v_lshlrev_b32_e32 v146, 1, v158
	v_add_f32_e32 v86, 1.0, v86
	v_lshl_add_u64 v[84:85], v[84:85], 0, v[146:147]
	v_rcp_f32_e32 v87, v86
	s_nop 0
	v_mul_f32_e32 v86, v78, v87
	v_mul_f32_e32 v87, 0x3d372713, v74
	v_mul_f32_e32 v87, v74, v87
	v_fma_f32 v87, v74, v87, v74
	v_mul_f32_e32 v87, 0xbfcc422a, v87
	v_mul_f32_e32 v87, 0x3fb8aa3b, v87
	v_exp_f32_e32 v87, v87
	s_nop 0
	v_add_f32_e32 v87, 1.0, v87
	s_nop 0
	v_rcp_f32_e32 v88, v87
	s_nop 0
	v_mul_f32_e32 v88, v74, v88
	v_mul_f32_e32 v87, 0x3d372713, v79
	v_mul_f32_e32 v87, v79, v87
	v_fma_f32 v87, v79, v87, v79
	v_mul_f32_e32 v87, 0xbfcc422a, v87
	v_mul_f32_e32 v87, 0x3fb8aa3b, v87
	v_exp_f32_e32 v87, v87
	s_nop 0
	v_add_f32_e32 v87, 1.0, v87
	s_nop 0
	v_rcp_f32_e32 v89, v87
	s_nop 0
	v_mul_f32_e32 v87, v79, v89
	v_mul_f32_e32 v89, 0x3d372713, v75
	v_mul_f32_e32 v89, v75, v89
	v_fma_f32 v89, v75, v89, v75
	v_mul_f32_e32 v89, 0xbfcc422a, v89
	v_mul_f32_e32 v89, 0x3fb8aa3b, v89
	v_exp_f32_e32 v89, v89
	v_cvt_pk_bf16_f32 v86, v86, v87
	s_nop 0
	v_add_f32_e32 v89, 1.0, v89
	s_nop 0
	v_rcp_f32_e32 v91, v89
	s_nop 0
	v_mul_f32_e32 v89, v75, v91
	v_mul_f32_e32 v91, 0x3d372713, v80
	v_mul_f32_e32 v91, v80, v91
	v_fma_f32 v91, v80, v91, v80
	v_mul_f32_e32 v91, 0xbfcc422a, v91
	v_mul_f32_e32 v91, 0x3fb8aa3b, v91
	v_exp_f32_e32 v91, v91
	s_nop 0
	v_add_f32_e32 v91, 1.0, v91
	s_nop 0
	v_rcp_f32_e32 v92, v91
	s_nop 0
	v_mul_f32_e32 v91, v80, v92
	v_mul_f32_e32 v92, 0x3d372713, v76
	v_mul_f32_e32 v92, v76, v92
	v_fma_f32 v92, v76, v92, v76
	v_mul_f32_e32 v92, 0xbfcc422a, v92
	v_mul_f32_e32 v92, 0x3fb8aa3b, v92
	v_exp_f32_e32 v92, v92
	s_nop 0
	v_add_f32_e32 v92, 1.0, v92
	s_nop 0
	v_rcp_f32_e32 v93, v92
	s_nop 0
	v_mul_f32_e32 v92, v76, v93
	v_mul_f32_e32 v93, 0x3d372713, v81
	v_mul_f32_e32 v93, v81, v93
	v_fma_f32 v93, v81, v93, v81
	v_mul_f32_e32 v93, 0xbfcc422a, v93
	v_mul_f32_e32 v93, 0x3fb8aa3b, v93
	v_exp_f32_e32 v93, v93
	s_nop 0
	v_add_f32_e32 v93, 1.0, v93
	s_nop 0
	v_rcp_f32_e32 v94, v93
	s_nop 0
	v_mul_f32_e32 v93, v81, v94
	v_mul_f32_e32 v94, 0x3d372713, v77
	v_mul_f32_e32 v94, v77, v94
	v_fma_f32 v94, v77, v94, v77
	v_mul_f32_e32 v94, 0xbfcc422a, v94
	v_mul_f32_e32 v94, 0x3fb8aa3b, v94
	v_exp_f32_e32 v94, v94
	v_cvt_pk_bf16_f32 v87, v91, v93
	v_cvt_pk_bf16_f32 v88, v88, v89
	s_nop 0
	v_add_f32_e32 v94, 1.0, v94
	s_nop 0
	v_rcp_f32_e32 v95, v94
	s_nop 0
	v_mul_f32_e32 v94, v77, v95
	v_cvt_pk_bf16_f32 v89, v92, v94
	global_store_dwordx4 v[84:85], v[86:89], off
	s_nop 1
	v_mul_f32_e32 v86, 0x3d372713, v70
	v_mul_f32_e32 v86, v70, v86
	v_fma_f32 v86, v70, v86, v70
	v_mul_f32_e32 v86, 0xbfcc422a, v86
	v_mul_f32_e32 v86, 0x3fb8aa3b, v86
	v_exp_f32_e32 v86, v86
	s_nop 0
	v_add_f32_e32 v86, 1.0, v86
	s_nop 0
	v_rcp_f32_e32 v87, v86
	s_nop 0
	v_mul_f32_e32 v86, v70, v87
	v_mul_f32_e32 v87, 0x3d372713, v66
	v_mul_f32_e32 v87, v66, v87
	v_fma_f32 v87, v66, v87, v66
	v_mul_f32_e32 v87, 0xbfcc422a, v87
	v_mul_f32_e32 v87, 0x3fb8aa3b, v87
	v_exp_f32_e32 v87, v87
	s_nop 0
	v_add_f32_e32 v87, 1.0, v87
	s_nop 0
	v_rcp_f32_e32 v88, v87
	s_nop 0
	v_mul_f32_e32 v88, v66, v88
	v_mul_f32_e32 v87, 0x3d372713, v71
	v_mul_f32_e32 v87, v71, v87
	v_fma_f32 v87, v71, v87, v71
	v_mul_f32_e32 v87, 0xbfcc422a, v87
	v_mul_f32_e32 v87, 0x3fb8aa3b, v87
	v_exp_f32_e32 v87, v87
	s_nop 0
	v_add_f32_e32 v87, 1.0, v87
	s_nop 0
	v_rcp_f32_e32 v89, v87
	s_nop 0
	v_mul_f32_e32 v87, v71, v89
	v_mul_f32_e32 v89, 0x3d372713, v67
	v_mul_f32_e32 v89, v67, v89
	v_fma_f32 v89, v67, v89, v67
	v_mul_f32_e32 v89, 0xbfcc422a, v89
	v_mul_f32_e32 v89, 0x3fb8aa3b, v89
	v_exp_f32_e32 v89, v89
	v_cvt_pk_bf16_f32 v86, v86, v87
	s_nop 0
	v_add_f32_e32 v89, 1.0, v89
	s_nop 0
	v_rcp_f32_e32 v91, v89
	s_nop 0
	v_mul_f32_e32 v89, v67, v91
	v_mul_f32_e32 v91, 0x3d372713, v72
	v_mul_f32_e32 v91, v72, v91
	v_fma_f32 v91, v72, v91, v72
	v_mul_f32_e32 v91, 0xbfcc422a, v91
	v_mul_f32_e32 v91, 0x3fb8aa3b, v91
	v_exp_f32_e32 v91, v91
	s_nop 0
	v_add_f32_e32 v91, 1.0, v91
	s_nop 0
	v_rcp_f32_e32 v92, v91
	s_nop 0
	v_mul_f32_e32 v91, v72, v92
	v_mul_f32_e32 v92, 0x3d372713, v68
	v_mul_f32_e32 v92, v68, v92
	v_fma_f32 v92, v68, v92, v68
	v_mul_f32_e32 v92, 0xbfcc422a, v92
	v_mul_f32_e32 v92, 0x3fb8aa3b, v92
	v_exp_f32_e32 v92, v92
	s_nop 0
	v_add_f32_e32 v92, 1.0, v92
	s_nop 0
	v_rcp_f32_e32 v93, v92
	s_nop 0
	v_mul_f32_e32 v92, v68, v93
	v_mul_f32_e32 v93, 0x3d372713, v73
	v_mul_f32_e32 v93, v73, v93
	v_fma_f32 v93, v73, v93, v73
	v_mul_f32_e32 v93, 0xbfcc422a, v93
	v_mul_f32_e32 v93, 0x3fb8aa3b, v93
	v_exp_f32_e32 v93, v93
	s_nop 0
	v_add_f32_e32 v93, 1.0, v93
	s_nop 0
	v_rcp_f32_e32 v94, v93
	s_nop 0
	v_mul_f32_e32 v93, v73, v94
	v_mul_f32_e32 v94, 0x3d372713, v69
	v_mul_f32_e32 v94, v69, v94
	v_fma_f32 v94, v69, v94, v69
	v_mul_f32_e32 v94, 0xbfcc422a, v94
	v_mul_f32_e32 v94, 0x3fb8aa3b, v94
	v_exp_f32_e32 v94, v94
	v_cvt_pk_bf16_f32 v87, v91, v93
	v_cvt_pk_bf16_f32 v88, v88, v89
	s_nop 0
	v_add_f32_e32 v94, 1.0, v94
	s_mov_b64 s[30:31], 0
	v_rcp_f32_e32 v95, v94
	s_nop 0
	v_mul_f32_e32 v94, v69, v95
	v_cvt_pk_bf16_f32 v89, v92, v94
	global_store_dwordx4 v[84:85], v[86:89], off offset:256

.LBB0_197:
	v_add_u32_e32 v82, 0xffffc080, v170
	s_nop 0
	v_ashrrev_i32_e32 v66, 4, v82
	v_add_u32_e32 v80, 0x80, v170
	v_add_u32_e32 v66, s17, v66
	v_mad_i64_i32 v[74:75], s[28:29], v66, s71, 0
	v_ashrrev_i32_e32 v66, 10, v80
	v_and_b32_e32 v66, -4, v66
	v_add_u32_e32 v66, s17, v66
	v_ashrrev_i32_e32 v67, 31, v66
	v_lshlrev_b64 v[76:77], 21, v[66:67]
	s_and_b64 vcc, exec, s[14:15]
	s_mov_b64 s[28:29], -1
	s_cbranch_vccnz .LBB0_207
	s_and_b64 vcc, exec, s[12:13]
	s_cbranch_vccnz .LBB0_204
	v_ashrrev_i32_e32 v81, 31, v80
	v_lshlrev_b64 v[66:67], 12, v[80:81]
	s_andn2_b64 vcc, exec, s[18:19]
	s_cbranch_vccnz .LBB0_201
	v_mul_f32_e32 v70, 0x3d372713, v62
	v_mul_f32_e32 v70, v62, v70
	v_fma_f32 v70, v62, v70, v62
	v_mul_f32_e32 v70, 0xbfcc422a, v70
	v_mul_f32_e32 v70, 0x3fb8aa3b, v70
	v_exp_f32_e32 v70, v70
	v_lshl_add_u64 v[68:69], s[48:49], 0, v[66:67]
	v_lshl_add_u64 v[68:69], s[56:57], 1, v[68:69]
	v_lshlrev_b32_e32 v146, 1, v158
	v_add_f32_e32 v70, 1.0, v70
	v_lshl_add_u64 v[68:69], v[68:69], 0, v[146:147]
	v_rcp_f32_e32 v71, v70
	s_nop 0
	v_mul_f32_e32 v70, v62, v71
	v_mul_f32_e32 v71, 0x3d372713, v58
	v_mul_f32_e32 v71, v58, v71
	v_fma_f32 v71, v58, v71, v58
	v_mul_f32_e32 v71, 0xbfcc422a, v71
	v_mul_f32_e32 v71, 0x3fb8aa3b, v71
	v_exp_f32_e32 v71, v71
	s_nop 0
	v_add_f32_e32 v71, 1.0, v71
	s_nop 0
	v_rcp_f32_e32 v72, v71
	s_nop 0
	v_mul_f32_e32 v72, v58, v72
	v_mul_f32_e32 v71, 0x3d372713, v63
	v_mul_f32_e32 v71, v63, v71
	v_fma_f32 v71, v63, v71, v63
	v_mul_f32_e32 v71, 0xbfcc422a, v71
	v_mul_f32_e32 v71, 0x3fb8aa3b, v71
	v_exp_f32_e32 v71, v71
	s_nop 0
	v_add_f32_e32 v71, 1.0, v71
	s_nop 0
	v_rcp_f32_e32 v73, v71
	s_nop 0
	v_mul_f32_e32 v71, v63, v73
	v_mul_f32_e32 v73, 0x3d372713, v59
	v_mul_f32_e32 v73, v59, v73
	v_fma_f32 v73, v59, v73, v59
	v_mul_f32_e32 v73, 0xbfcc422a, v73
	v_mul_f32_e32 v73, 0x3fb8aa3b, v73
	v_exp_f32_e32 v73, v73
	v_cvt_pk_bf16_f32 v70, v70, v71
	s_nop 0
	v_add_f32_e32 v73, 1.0, v73
	s_nop 0
	v_rcp_f32_e32 v78, v73
	s_nop 0
	v_mul_f32_e32 v73, v59, v78
	v_mul_f32_e32 v78, 0x3d372713, v64
	v_mul_f32_e32 v78, v64, v78
	v_fma_f32 v78, v64, v78, v64
	v_mul_f32_e32 v78, 0xbfcc422a, v78
	v_mul_f32_e32 v78, 0x3fb8aa3b, v78
	v_exp_f32_e32 v78, v78
	s_nop 0
	v_add_f32_e32 v78, 1.0, v78
	s_nop 0
	v_rcp_f32_e32 v79, v78
	s_nop 0
	v_mul_f32_e32 v78, v64, v79
	v_mul_f32_e32 v79, 0x3d372713, v60
	v_mul_f32_e32 v79, v60, v79
	v_fma_f32 v79, v60, v79, v60
	v_mul_f32_e32 v79, 0xbfcc422a, v79
	v_mul_f32_e32 v79, 0x3fb8aa3b, v79
	v_exp_f32_e32 v79, v79
	s_nop 0
	v_add_f32_e32 v79, 1.0, v79
	s_nop 0
	v_rcp_f32_e32 v81, v79
	s_nop 0
	v_mul_f32_e32 v79, v60, v81
	v_mul_f32_e32 v81, 0x3d372713, v65
	v_mul_f32_e32 v81, v65, v81
	v_fma_f32 v81, v65, v81, v65
	v_mul_f32_e32 v81, 0xbfcc422a, v81
	v_mul_f32_e32 v81, 0x3fb8aa3b, v81
	v_exp_f32_e32 v81, v81
	s_nop 0
	v_add_f32_e32 v81, 1.0, v81
	s_nop 0
	v_rcp_f32_e32 v83, v81
	s_nop 0
	v_mul_f32_e32 v81, v65, v83
	v_mul_f32_e32 v83, 0x3d372713, v61
	v_mul_f32_e32 v83, v61, v83
	v_fma_f32 v83, v61, v83, v61
	v_mul_f32_e32 v83, 0xbfcc422a, v83
	v_mul_f32_e32 v83, 0x3fb8aa3b, v83
	v_exp_f32_e32 v83, v83
	v_cvt_pk_bf16_f32 v71, v78, v81
	v_cvt_pk_bf16_f32 v72, v72, v73
	s_nop 0
	v_add_f32_e32 v83, 1.0, v83
	s_nop 0
	v_rcp_f32_e32 v84, v83
	s_nop 0
	v_mul_f32_e32 v83, v61, v84
	v_cvt_pk_bf16_f32 v73, v79, v83
	global_store_dwordx4 v[68:69], v[70:73], off
	s_nop 1
	v_mul_f32_e32 v70, 0x3d372713, v54
	v_mul_f32_e32 v70, v54, v70
	v_fma_f32 v70, v54, v70, v54
	v_mul_f32_e32 v70, 0xbfcc422a, v70
	v_mul_f32_e32 v70, 0x3fb8aa3b, v70
	v_exp_f32_e32 v70, v70
	s_nop 0
	v_add_f32_e32 v70, 1.0, v70
	s_nop 0
	v_rcp_f32_e32 v71, v70
	s_nop 0
	v_mul_f32_e32 v70, v54, v71
	v_mul_f32_e32 v71, 0x3d372713, v50
	v_mul_f32_e32 v71, v50, v71
	v_fma_f32 v71, v50, v71, v50
	v_mul_f32_e32 v71, 0xbfcc422a, v71
	v_mul_f32_e32 v71, 0x3fb8aa3b, v71
	v_exp_f32_e32 v71, v71
	s_nop 0
	v_add_f32_e32 v71, 1.0, v71
	s_nop 0
	v_rcp_f32_e32 v72, v71
	s_nop 0
	v_mul_f32_e32 v72, v50, v72
	v_mul_f32_e32 v71, 0x3d372713, v55
	v_mul_f32_e32 v71, v55, v71
	v_fma_f32 v71, v55, v71, v55
	v_mul_f32_e32 v71, 0xbfcc422a, v71
	v_mul_f32_e32 v71, 0x3fb8aa3b, v71
	v_exp_f32_e32 v71, v71
	s_nop 0
	v_add_f32_e32 v71, 1.0, v71
	s_nop 0
	v_rcp_f32_e32 v73, v71
	s_nop 0
	v_mul_f32_e32 v71, v55, v73
	v_mul_f32_e32 v73, 0x3d372713, v51
	v_mul_f32_e32 v73, v51, v73
	v_fma_f32 v73, v51, v73, v51
	v_mul_f32_e32 v73, 0xbfcc422a, v73
	v_mul_f32_e32 v73, 0x3fb8aa3b, v73
	v_exp_f32_e32 v73, v73
	v_cvt_pk_bf16_f32 v70, v70, v71
	s_nop 0
	v_add_f32_e32 v73, 1.0, v73
	s_nop 0
	v_rcp_f32_e32 v78, v73
	s_nop 0
	v_mul_f32_e32 v73, v51, v78
	v_mul_f32_e32 v78, 0x3d372713, v56
	v_mul_f32_e32 v78, v56, v78
	v_fma_f32 v78, v56, v78, v56
	v_mul_f32_e32 v78, 0xbfcc422a, v78
	v_mul_f32_e32 v78, 0x3fb8aa3b, v78
	v_exp_f32_e32 v78, v78
	s_nop 0
	v_add_f32_e32 v78, 1.0, v78
	s_nop 0
	v_rcp_f32_e32 v79, v78
	s_nop 0
	v_mul_f32_e32 v78, v56, v79
	v_mul_f32_e32 v79, 0x3d372713, v52
	v_mul_f32_e32 v79, v52, v79
	v_fma_f32 v79, v52, v79, v52
	v_mul_f32_e32 v79, 0xbfcc422a, v79
	v_mul_f32_e32 v79, 0x3fb8aa3b, v79
	v_exp_f32_e32 v79, v79
	s_nop 0
	v_add_f32_e32 v79, 1.0, v79
	s_nop 0
	v_rcp_f32_e32 v81, v79
	s_nop 0
	v_mul_f32_e32 v79, v52, v81
	v_mul_f32_e32 v81, 0x3d372713, v57
	v_mul_f32_e32 v81, v57, v81
	v_fma_f32 v81, v57, v81, v57
	v_mul_f32_e32 v81, 0xbfcc422a, v81
	v_mul_f32_e32 v81, 0x3fb8aa3b, v81
	v_exp_f32_e32 v81, v81
	s_nop 0
	v_add_f32_e32 v81, 1.0, v81
	s_nop 0
	v_rcp_f32_e32 v83, v81
	s_nop 0
	v_mul_f32_e32 v81, v57, v83
	v_mul_f32_e32 v83, 0x3d372713, v53
	v_mul_f32_e32 v83, v53, v83
	v_fma_f32 v83, v53, v83, v53
	v_mul_f32_e32 v83, 0xbfcc422a, v83
	v_mul_f32_e32 v83, 0x3fb8aa3b, v83
	v_exp_f32_e32 v83, v83
	v_cvt_pk_bf16_f32 v71, v78, v81
	v_cvt_pk_bf16_f32 v72, v72, v73
	s_nop 0
	v_add_f32_e32 v83, 1.0, v83
	s_mov_b64 s[28:29], 0
	v_rcp_f32_e32 v84, v83
	s_nop 0
	v_mul_f32_e32 v83, v53, v84
	v_cvt_pk_bf16_f32 v73, v79, v83
	global_store_dwordx4 v[68:69], v[70:73], off offset:256

.LBB0_214:
	v_add_u32_e32 v58, 0x90, v170
	s_and_b64 vcc, exec, s[14:15]
	s_mov_b64 s[28:29], -1
	s_cbranch_vccnz .LBB0_224
	s_and_b64 vcc, exec, s[12:13]
	s_cbranch_vccnz .LBB0_221
	v_ashrrev_i32_e32 v59, 31, v58
	v_lshlrev_b64 v[50:51], 12, v[58:59]
	s_andn2_b64 vcc, exec, s[18:19]
	s_cbranch_vccnz .LBB0_218
	v_mul_f32_e32 v54, 0x3d372713, v46
	v_mul_f32_e32 v54, v46, v54
	v_fma_f32 v54, v46, v54, v46
	v_mul_f32_e32 v54, 0xbfcc422a, v54
	v_mul_f32_e32 v54, 0x3fb8aa3b, v54
	v_exp_f32_e32 v54, v54
	v_lshl_add_u64 v[52:53], s[48:49], 0, v[50:51]
	v_lshl_add_u64 v[52:53], s[56:57], 1, v[52:53]
	v_lshlrev_b32_e32 v146, 1, v158
	v_add_f32_e32 v54, 1.0, v54
	v_lshl_add_u64 v[52:53], v[52:53], 0, v[146:147]
	v_rcp_f32_e32 v55, v54
	s_nop 0
	v_mul_f32_e32 v54, v46, v55
	v_mul_f32_e32 v55, 0x3d372713, v42
	v_mul_f32_e32 v55, v42, v55
	v_fma_f32 v55, v42, v55, v42
	v_mul_f32_e32 v55, 0xbfcc422a, v55
	v_mul_f32_e32 v55, 0x3fb8aa3b, v55
	v_exp_f32_e32 v55, v55
	s_nop 0
	v_add_f32_e32 v55, 1.0, v55
	s_nop 0
	v_rcp_f32_e32 v56, v55
	s_nop 0
	v_mul_f32_e32 v56, v42, v56
	v_mul_f32_e32 v55, 0x3d372713, v47
	v_mul_f32_e32 v55, v47, v55
	v_fma_f32 v55, v47, v55, v47
	v_mul_f32_e32 v55, 0xbfcc422a, v55
	v_mul_f32_e32 v55, 0x3fb8aa3b, v55
	v_exp_f32_e32 v55, v55
	s_nop 0
	v_add_f32_e32 v55, 1.0, v55
	s_nop 0
	v_rcp_f32_e32 v57, v55
	s_nop 0
	v_mul_f32_e32 v55, v47, v57
	v_mul_f32_e32 v57, 0x3d372713, v43
	v_mul_f32_e32 v57, v43, v57
	v_fma_f32 v57, v43, v57, v43
	v_mul_f32_e32 v57, 0xbfcc422a, v57
	v_mul_f32_e32 v57, 0x3fb8aa3b, v57
	v_exp_f32_e32 v57, v57
	v_cvt_pk_bf16_f32 v54, v54, v55
	s_nop 0
	v_add_f32_e32 v57, 1.0, v57
	s_nop 0
	v_rcp_f32_e32 v59, v57
	s_nop 0
	v_mul_f32_e32 v57, v43, v59
	v_mul_f32_e32 v59, 0x3d372713, v48
	v_mul_f32_e32 v59, v48, v59
	v_fma_f32 v59, v48, v59, v48
	v_mul_f32_e32 v59, 0xbfcc422a, v59
	v_mul_f32_e32 v59, 0x3fb8aa3b, v59
	v_exp_f32_e32 v59, v59
	s_nop 0
	v_add_f32_e32 v59, 1.0, v59
	s_nop 0
	v_rcp_f32_e32 v60, v59
	s_nop 0
	v_mul_f32_e32 v59, v48, v60
	v_mul_f32_e32 v60, 0x3d372713, v44
	v_mul_f32_e32 v60, v44, v60
	v_fma_f32 v60, v44, v60, v44
	v_mul_f32_e32 v60, 0xbfcc422a, v60
	v_mul_f32_e32 v60, 0x3fb8aa3b, v60
	v_exp_f32_e32 v60, v60
	s_nop 0
	v_add_f32_e32 v60, 1.0, v60
	s_nop 0
	v_rcp_f32_e32 v61, v60
	s_nop 0
	v_mul_f32_e32 v60, v44, v61
	v_mul_f32_e32 v61, 0x3d372713, v49
	v_mul_f32_e32 v61, v49, v61
	v_fma_f32 v61, v49, v61, v49
	v_mul_f32_e32 v61, 0xbfcc422a, v61
	v_mul_f32_e32 v61, 0x3fb8aa3b, v61
	v_exp_f32_e32 v61, v61
	s_nop 0
	v_add_f32_e32 v61, 1.0, v61
	s_nop 0
	v_rcp_f32_e32 v62, v61
	s_nop 0
	v_mul_f32_e32 v61, v49, v62
	v_mul_f32_e32 v62, 0x3d372713, v45
	v_mul_f32_e32 v62, v45, v62
	v_fma_f32 v62, v45, v62, v45
	v_mul_f32_e32 v62, 0xbfcc422a, v62
	v_mul_f32_e32 v62, 0x3fb8aa3b, v62
	v_exp_f32_e32 v62, v62
	v_cvt_pk_bf16_f32 v55, v59, v61
	v_cvt_pk_bf16_f32 v56, v56, v57
	s_nop 0
	v_add_f32_e32 v62, 1.0, v62
	s_nop 0
	v_rcp_f32_e32 v63, v62
	s_nop 0
	v_mul_f32_e32 v62, v45, v63
	v_cvt_pk_bf16_f32 v57, v60, v62
	global_store_dwordx4 v[52:53], v[54:57], off
	s_nop 1
	v_mul_f32_e32 v54, 0x3d372713, v38
	v_mul_f32_e32 v54, v38, v54
	v_fma_f32 v54, v38, v54, v38
	v_mul_f32_e32 v54, 0xbfcc422a, v54
	v_mul_f32_e32 v54, 0x3fb8aa3b, v54
	v_exp_f32_e32 v54, v54
	s_nop 0
	v_add_f32_e32 v54, 1.0, v54
	s_nop 0
	v_rcp_f32_e32 v55, v54
	s_nop 0
	v_mul_f32_e32 v54, v38, v55
	v_mul_f32_e32 v55, 0x3d372713, v34
	v_mul_f32_e32 v55, v34, v55
	v_fma_f32 v55, v34, v55, v34
	v_mul_f32_e32 v55, 0xbfcc422a, v55
	v_mul_f32_e32 v55, 0x3fb8aa3b, v55
	v_exp_f32_e32 v55, v55
	s_nop 0
	v_add_f32_e32 v55, 1.0, v55
	s_nop 0
	v_rcp_f32_e32 v56, v55
	s_nop 0
	v_mul_f32_e32 v56, v34, v56
	v_mul_f32_e32 v55, 0x3d372713, v39
	v_mul_f32_e32 v55, v39, v55
	v_fma_f32 v55, v39, v55, v39
	v_mul_f32_e32 v55, 0xbfcc422a, v55
	v_mul_f32_e32 v55, 0x3fb8aa3b, v55
	v_exp_f32_e32 v55, v55
	s_nop 0
	v_add_f32_e32 v55, 1.0, v55
	s_nop 0
	v_rcp_f32_e32 v57, v55
	s_nop 0
	v_mul_f32_e32 v55, v39, v57
	v_mul_f32_e32 v57, 0x3d372713, v35
	v_mul_f32_e32 v57, v35, v57
	v_fma_f32 v57, v35, v57, v35
	v_mul_f32_e32 v57, 0xbfcc422a, v57
	v_mul_f32_e32 v57, 0x3fb8aa3b, v57
	v_exp_f32_e32 v57, v57
	v_cvt_pk_bf16_f32 v54, v54, v55
	s_nop 0
	v_add_f32_e32 v57, 1.0, v57
	s_nop 0
	v_rcp_f32_e32 v59, v57
	s_nop 0
	v_mul_f32_e32 v57, v35, v59
	v_mul_f32_e32 v59, 0x3d372713, v40
	v_mul_f32_e32 v59, v40, v59
	v_fma_f32 v59, v40, v59, v40
	v_mul_f32_e32 v59, 0xbfcc422a, v59
	v_mul_f32_e32 v59, 0x3fb8aa3b, v59
	v_exp_f32_e32 v59, v59
	s_nop 0
	v_add_f32_e32 v59, 1.0, v59
	s_nop 0
	v_rcp_f32_e32 v60, v59
	s_nop 0
	v_mul_f32_e32 v59, v40, v60
	v_mul_f32_e32 v60, 0x3d372713, v36
	v_mul_f32_e32 v60, v36, v60
	v_fma_f32 v60, v36, v60, v36
	v_mul_f32_e32 v60, 0xbfcc422a, v60
	v_mul_f32_e32 v60, 0x3fb8aa3b, v60
	v_exp_f32_e32 v60, v60
	s_nop 0
	v_add_f32_e32 v60, 1.0, v60
	s_nop 0
	v_rcp_f32_e32 v61, v60
	s_nop 0
	v_mul_f32_e32 v60, v36, v61
	v_mul_f32_e32 v61, 0x3d372713, v41
	v_mul_f32_e32 v61, v41, v61
	v_fma_f32 v61, v41, v61, v41
	v_mul_f32_e32 v61, 0xbfcc422a, v61
	v_mul_f32_e32 v61, 0x3fb8aa3b, v61
	v_exp_f32_e32 v61, v61
	s_nop 0
	v_add_f32_e32 v61, 1.0, v61
	s_nop 0
	v_rcp_f32_e32 v62, v61
	s_nop 0
	v_mul_f32_e32 v61, v41, v62
	v_mul_f32_e32 v62, 0x3d372713, v37
	v_mul_f32_e32 v62, v37, v62
	v_fma_f32 v62, v37, v62, v37
	v_mul_f32_e32 v62, 0xbfcc422a, v62
	v_mul_f32_e32 v62, 0x3fb8aa3b, v62
	v_exp_f32_e32 v62, v62
	v_cvt_pk_bf16_f32 v55, v59, v61
	v_cvt_pk_bf16_f32 v56, v56, v57
	s_nop 0
	v_add_f32_e32 v62, 1.0, v62
	s_mov_b64 s[28:29], 0
	v_rcp_f32_e32 v63, v62
	s_nop 0
	v_mul_f32_e32 v62, v37, v63
	v_cvt_pk_bf16_f32 v57, v60, v62
	global_store_dwordx4 v[52:53], v[54:57], off offset:256

.LBB0_231:
	v_add_u32_e32 v42, 0xa0, v170
	s_and_b64 vcc, exec, s[14:15]
	s_mov_b64 s[28:29], -1
	s_cbranch_vccnz .LBB0_241
	s_and_b64 vcc, exec, s[12:13]
	s_cbranch_vccnz .LBB0_238
	v_ashrrev_i32_e32 v43, 31, v42
	v_lshlrev_b64 v[34:35], 12, v[42:43]
	s_andn2_b64 vcc, exec, s[18:19]
	s_cbranch_vccnz .LBB0_235
	v_mul_f32_e32 v38, 0x3d372713, v30
	v_mul_f32_e32 v38, v30, v38
	v_fma_f32 v38, v30, v38, v30
	v_mul_f32_e32 v38, 0xbfcc422a, v38
	v_mul_f32_e32 v38, 0x3fb8aa3b, v38
	v_exp_f32_e32 v38, v38
	v_lshl_add_u64 v[36:37], s[48:49], 0, v[34:35]
	v_lshl_add_u64 v[36:37], s[56:57], 1, v[36:37]
	v_lshlrev_b32_e32 v146, 1, v158
	v_add_f32_e32 v38, 1.0, v38
	v_lshl_add_u64 v[36:37], v[36:37], 0, v[146:147]
	v_rcp_f32_e32 v39, v38
	s_nop 0
	v_mul_f32_e32 v38, v30, v39
	v_mul_f32_e32 v39, 0x3d372713, v26
	v_mul_f32_e32 v39, v26, v39
	v_fma_f32 v39, v26, v39, v26
	v_mul_f32_e32 v39, 0xbfcc422a, v39
	v_mul_f32_e32 v39, 0x3fb8aa3b, v39
	v_exp_f32_e32 v39, v39
	s_nop 0
	v_add_f32_e32 v39, 1.0, v39
	s_nop 0
	v_rcp_f32_e32 v40, v39
	s_nop 0
	v_mul_f32_e32 v40, v26, v40
	v_mul_f32_e32 v39, 0x3d372713, v31
	v_mul_f32_e32 v39, v31, v39
	v_fma_f32 v39, v31, v39, v31
	v_mul_f32_e32 v39, 0xbfcc422a, v39
	v_mul_f32_e32 v39, 0x3fb8aa3b, v39
	v_exp_f32_e32 v39, v39
	s_nop 0
	v_add_f32_e32 v39, 1.0, v39
	s_nop 0
	v_rcp_f32_e32 v41, v39
	s_nop 0
	v_mul_f32_e32 v39, v31, v41
	v_mul_f32_e32 v41, 0x3d372713, v27
	v_mul_f32_e32 v41, v27, v41
	v_fma_f32 v41, v27, v41, v27
	v_mul_f32_e32 v41, 0xbfcc422a, v41
	v_mul_f32_e32 v41, 0x3fb8aa3b, v41
	v_exp_f32_e32 v41, v41
	v_cvt_pk_bf16_f32 v38, v38, v39
	s_nop 0
	v_add_f32_e32 v41, 1.0, v41
	s_nop 0
	v_rcp_f32_e32 v43, v41
	s_nop 0
	v_mul_f32_e32 v41, v27, v43
	v_mul_f32_e32 v43, 0x3d372713, v32
	v_mul_f32_e32 v43, v32, v43
	v_fma_f32 v43, v32, v43, v32
	v_mul_f32_e32 v43, 0xbfcc422a, v43
	v_mul_f32_e32 v43, 0x3fb8aa3b, v43
	v_exp_f32_e32 v43, v43
	s_nop 0
	v_add_f32_e32 v43, 1.0, v43
	s_nop 0
	v_rcp_f32_e32 v44, v43
	s_nop 0
	v_mul_f32_e32 v43, v32, v44
	v_mul_f32_e32 v44, 0x3d372713, v28
	v_mul_f32_e32 v44, v28, v44
	v_fma_f32 v44, v28, v44, v28
	v_mul_f32_e32 v44, 0xbfcc422a, v44
	v_mul_f32_e32 v44, 0x3fb8aa3b, v44
	v_exp_f32_e32 v44, v44
	s_nop 0
	v_add_f32_e32 v44, 1.0, v44
	s_nop 0
	v_rcp_f32_e32 v45, v44
	s_nop 0
	v_mul_f32_e32 v44, v28, v45
	v_mul_f32_e32 v45, 0x3d372713, v33
	v_mul_f32_e32 v45, v33, v45
	v_fma_f32 v45, v33, v45, v33
	v_mul_f32_e32 v45, 0xbfcc422a, v45
	v_mul_f32_e32 v45, 0x3fb8aa3b, v45
	v_exp_f32_e32 v45, v45
	s_nop 0
	v_add_f32_e32 v45, 1.0, v45
	s_nop 0
	v_rcp_f32_e32 v46, v45
	s_nop 0
	v_mul_f32_e32 v45, v33, v46
	v_mul_f32_e32 v46, 0x3d372713, v29
	v_mul_f32_e32 v46, v29, v46
	v_fma_f32 v46, v29, v46, v29
	v_mul_f32_e32 v46, 0xbfcc422a, v46
	v_mul_f32_e32 v46, 0x3fb8aa3b, v46
	v_exp_f32_e32 v46, v46
	v_cvt_pk_bf16_f32 v39, v43, v45
	v_cvt_pk_bf16_f32 v40, v40, v41
	s_nop 0
	v_add_f32_e32 v46, 1.0, v46
	s_nop 0
	v_rcp_f32_e32 v47, v46
	s_nop 0
	v_mul_f32_e32 v46, v29, v47
	v_cvt_pk_bf16_f32 v41, v44, v46
	global_store_dwordx4 v[36:37], v[38:41], off
	s_nop 1
	v_mul_f32_e32 v38, 0x3d372713, v22
	v_mul_f32_e32 v38, v22, v38
	v_fma_f32 v38, v22, v38, v22
	v_mul_f32_e32 v38, 0xbfcc422a, v38
	v_mul_f32_e32 v38, 0x3fb8aa3b, v38
	v_exp_f32_e32 v38, v38
	s_nop 0
	v_add_f32_e32 v38, 1.0, v38
	s_nop 0
	v_rcp_f32_e32 v39, v38
	s_nop 0
	v_mul_f32_e32 v38, v22, v39
	v_mul_f32_e32 v39, 0x3d372713, v18
	v_mul_f32_e32 v39, v18, v39
	v_fma_f32 v39, v18, v39, v18
	v_mul_f32_e32 v39, 0xbfcc422a, v39
	v_mul_f32_e32 v39, 0x3fb8aa3b, v39
	v_exp_f32_e32 v39, v39
	s_nop 0
	v_add_f32_e32 v39, 1.0, v39
	s_nop 0
	v_rcp_f32_e32 v40, v39
	s_nop 0
	v_mul_f32_e32 v40, v18, v40
	v_mul_f32_e32 v39, 0x3d372713, v23
	v_mul_f32_e32 v39, v23, v39
	v_fma_f32 v39, v23, v39, v23
	v_mul_f32_e32 v39, 0xbfcc422a, v39
	v_mul_f32_e32 v39, 0x3fb8aa3b, v39
	v_exp_f32_e32 v39, v39
	s_nop 0
	v_add_f32_e32 v39, 1.0, v39
	s_nop 0
	v_rcp_f32_e32 v41, v39
	s_nop 0
	v_mul_f32_e32 v39, v23, v41
	v_mul_f32_e32 v41, 0x3d372713, v19
	v_mul_f32_e32 v41, v19, v41
	v_fma_f32 v41, v19, v41, v19
	v_mul_f32_e32 v41, 0xbfcc422a, v41
	v_mul_f32_e32 v41, 0x3fb8aa3b, v41
	v_exp_f32_e32 v41, v41
	v_cvt_pk_bf16_f32 v38, v38, v39
	s_nop 0
	v_add_f32_e32 v41, 1.0, v41
	s_nop 0
	v_rcp_f32_e32 v43, v41
	s_nop 0
	v_mul_f32_e32 v41, v19, v43
	v_mul_f32_e32 v43, 0x3d372713, v24
	v_mul_f32_e32 v43, v24, v43
	v_fma_f32 v43, v24, v43, v24
	v_mul_f32_e32 v43, 0xbfcc422a, v43
	v_mul_f32_e32 v43, 0x3fb8aa3b, v43
	v_exp_f32_e32 v43, v43
	s_nop 0
	v_add_f32_e32 v43, 1.0, v43
	s_nop 0
	v_rcp_f32_e32 v44, v43
	s_nop 0
	v_mul_f32_e32 v43, v24, v44
	v_mul_f32_e32 v44, 0x3d372713, v20
	v_mul_f32_e32 v44, v20, v44
	v_fma_f32 v44, v20, v44, v20
	v_mul_f32_e32 v44, 0xbfcc422a, v44
	v_mul_f32_e32 v44, 0x3fb8aa3b, v44
	v_exp_f32_e32 v44, v44
	s_nop 0
	v_add_f32_e32 v44, 1.0, v44
	s_nop 0
	v_rcp_f32_e32 v45, v44
	s_nop 0
	v_mul_f32_e32 v44, v20, v45
	v_mul_f32_e32 v45, 0x3d372713, v25
	v_mul_f32_e32 v45, v25, v45
	v_fma_f32 v45, v25, v45, v25
	v_mul_f32_e32 v45, 0xbfcc422a, v45
	v_mul_f32_e32 v45, 0x3fb8aa3b, v45
	v_exp_f32_e32 v45, v45
	s_nop 0
	v_add_f32_e32 v45, 1.0, v45
	s_nop 0
	v_rcp_f32_e32 v46, v45
	s_nop 0
	v_mul_f32_e32 v45, v25, v46
	v_mul_f32_e32 v46, 0x3d372713, v21
	v_mul_f32_e32 v46, v21, v46
	v_fma_f32 v46, v21, v46, v21
	v_mul_f32_e32 v46, 0xbfcc422a, v46
	v_mul_f32_e32 v46, 0x3fb8aa3b, v46
	v_exp_f32_e32 v46, v46
	v_cvt_pk_bf16_f32 v39, v43, v45
	v_cvt_pk_bf16_f32 v40, v40, v41
	s_nop 0
	v_add_f32_e32 v46, 1.0, v46
	s_mov_b64 s[28:29], 0
	v_rcp_f32_e32 v47, v46
	s_nop 0
	v_mul_f32_e32 v46, v21, v47
	v_cvt_pk_bf16_f32 v41, v44, v46
	global_store_dwordx4 v[36:37], v[38:41], off offset:256

.LBB0_248:
	v_add_u32_e32 v26, 0xb0, v170
	s_and_b64 vcc, exec, s[14:15]
	s_mov_b64 s[14:15], -1
	s_cbranch_vccnz .LBB0_258
	s_and_b64 vcc, exec, s[12:13]
	s_mov_b64 s[12:13], -1
	s_cbranch_vccnz .LBB0_255
	v_ashrrev_i32_e32 v27, 31, v26
	v_lshlrev_b64 v[18:19], 12, v[26:27]
	s_andn2_b64 vcc, exec, s[18:19]
	s_cbranch_vccnz .LBB0_252
	v_mul_f32_e32 v22, 0x3d372713, v14
	v_mul_f32_e32 v22, v14, v22
	v_fma_f32 v22, v14, v22, v14
	v_mul_f32_e32 v22, 0xbfcc422a, v22
	v_mul_f32_e32 v22, 0x3fb8aa3b, v22
	v_exp_f32_e32 v22, v22
	v_lshl_add_u64 v[20:21], s[48:49], 0, v[18:19]
	v_lshl_add_u64 v[20:21], s[56:57], 1, v[20:21]
	v_lshlrev_b32_e32 v146, 1, v158
	v_add_f32_e32 v22, 1.0, v22
	v_lshl_add_u64 v[20:21], v[20:21], 0, v[146:147]
	v_rcp_f32_e32 v23, v22
	s_nop 0
	v_mul_f32_e32 v22, v14, v23
	v_mul_f32_e32 v23, 0x3d372713, v10
	v_mul_f32_e32 v23, v10, v23
	v_fma_f32 v23, v10, v23, v10
	v_mul_f32_e32 v23, 0xbfcc422a, v23
	v_mul_f32_e32 v23, 0x3fb8aa3b, v23
	v_exp_f32_e32 v23, v23
	s_nop 0
	v_add_f32_e32 v23, 1.0, v23
	s_nop 0
	v_rcp_f32_e32 v24, v23
	s_nop 0
	v_mul_f32_e32 v24, v10, v24
	v_mul_f32_e32 v23, 0x3d372713, v15
	v_mul_f32_e32 v23, v15, v23
	v_fma_f32 v23, v15, v23, v15
	v_mul_f32_e32 v23, 0xbfcc422a, v23
	v_mul_f32_e32 v23, 0x3fb8aa3b, v23
	v_exp_f32_e32 v23, v23
	s_nop 0
	v_add_f32_e32 v23, 1.0, v23
	s_nop 0
	v_rcp_f32_e32 v25, v23
	s_nop 0
	v_mul_f32_e32 v23, v15, v25
	v_mul_f32_e32 v25, 0x3d372713, v11
	v_mul_f32_e32 v25, v11, v25
	v_fma_f32 v25, v11, v25, v11
	v_mul_f32_e32 v25, 0xbfcc422a, v25
	v_mul_f32_e32 v25, 0x3fb8aa3b, v25
	v_exp_f32_e32 v25, v25
	v_cvt_pk_bf16_f32 v22, v22, v23
	s_nop 0
	v_add_f32_e32 v25, 1.0, v25
	s_nop 0
	v_rcp_f32_e32 v27, v25
	s_nop 0
	v_mul_f32_e32 v25, v11, v27
	v_mul_f32_e32 v27, 0x3d372713, v16
	v_mul_f32_e32 v27, v16, v27
	v_fma_f32 v27, v16, v27, v16
	v_mul_f32_e32 v27, 0xbfcc422a, v27
	v_mul_f32_e32 v27, 0x3fb8aa3b, v27
	v_exp_f32_e32 v27, v27
	s_nop 0
	v_add_f32_e32 v27, 1.0, v27
	s_nop 0
	v_rcp_f32_e32 v28, v27
	s_nop 0
	v_mul_f32_e32 v27, v16, v28
	v_mul_f32_e32 v28, 0x3d372713, v12
	v_mul_f32_e32 v28, v12, v28
	v_fma_f32 v28, v12, v28, v12
	v_mul_f32_e32 v28, 0xbfcc422a, v28
	v_mul_f32_e32 v28, 0x3fb8aa3b, v28
	v_exp_f32_e32 v28, v28
	s_nop 0
	v_add_f32_e32 v28, 1.0, v28
	s_nop 0
	v_rcp_f32_e32 v29, v28
	s_nop 0
	v_mul_f32_e32 v28, v12, v29
	v_mul_f32_e32 v29, 0x3d372713, v17
	v_mul_f32_e32 v29, v17, v29
	v_fma_f32 v29, v17, v29, v17
	v_mul_f32_e32 v29, 0xbfcc422a, v29
	v_mul_f32_e32 v29, 0x3fb8aa3b, v29
	v_exp_f32_e32 v29, v29
	s_nop 0
	v_add_f32_e32 v29, 1.0, v29
	s_nop 0
	v_rcp_f32_e32 v30, v29
	s_nop 0
	v_mul_f32_e32 v29, v17, v30
	v_mul_f32_e32 v30, 0x3d372713, v13
	v_mul_f32_e32 v30, v13, v30
	v_fma_f32 v30, v13, v30, v13
	v_mul_f32_e32 v30, 0xbfcc422a, v30
	v_mul_f32_e32 v30, 0x3fb8aa3b, v30
	v_exp_f32_e32 v30, v30
	v_cvt_pk_bf16_f32 v23, v27, v29
	v_cvt_pk_bf16_f32 v24, v24, v25
	s_nop 0
	v_add_f32_e32 v30, 1.0, v30
	s_nop 0
	v_rcp_f32_e32 v31, v30
	s_nop 0
	v_mul_f32_e32 v30, v13, v31
	v_cvt_pk_bf16_f32 v25, v28, v30
	global_store_dwordx4 v[20:21], v[22:25], off
	s_nop 1
	v_mul_f32_e32 v22, 0x3d372713, v6
	v_mul_f32_e32 v22, v6, v22
	v_fma_f32 v22, v6, v22, v6
	v_mul_f32_e32 v22, 0xbfcc422a, v22
	v_mul_f32_e32 v22, 0x3fb8aa3b, v22
	v_exp_f32_e32 v22, v22
	s_nop 0
	v_add_f32_e32 v22, 1.0, v22
	s_nop 0
	v_rcp_f32_e32 v23, v22
	s_nop 0
	v_mul_f32_e32 v22, v6, v23
	v_mul_f32_e32 v23, 0x3d372713, v2
	v_mul_f32_e32 v23, v2, v23
	v_fma_f32 v23, v2, v23, v2
	v_mul_f32_e32 v23, 0xbfcc422a, v23
	v_mul_f32_e32 v23, 0x3fb8aa3b, v23
	v_exp_f32_e32 v23, v23
	s_nop 0
	v_add_f32_e32 v23, 1.0, v23
	s_nop 0
	v_rcp_f32_e32 v24, v23
	s_nop 0
	v_mul_f32_e32 v24, v2, v24
	v_mul_f32_e32 v23, 0x3d372713, v7
	v_mul_f32_e32 v23, v7, v23
	v_fma_f32 v23, v7, v23, v7
	v_mul_f32_e32 v23, 0xbfcc422a, v23
	v_mul_f32_e32 v23, 0x3fb8aa3b, v23
	v_exp_f32_e32 v23, v23
	s_nop 0
	v_add_f32_e32 v23, 1.0, v23
	s_nop 0
	v_rcp_f32_e32 v25, v23
	s_nop 0
	v_mul_f32_e32 v23, v7, v25
	v_mul_f32_e32 v25, 0x3d372713, v3
	v_mul_f32_e32 v25, v3, v25
	v_fma_f32 v25, v3, v25, v3
	v_mul_f32_e32 v25, 0xbfcc422a, v25
	v_mul_f32_e32 v25, 0x3fb8aa3b, v25
	v_exp_f32_e32 v25, v25
	v_cvt_pk_bf16_f32 v22, v22, v23
	s_nop 0
	v_add_f32_e32 v25, 1.0, v25
	s_nop 0
	v_rcp_f32_e32 v27, v25
	s_nop 0
	v_mul_f32_e32 v25, v3, v27
	v_mul_f32_e32 v27, 0x3d372713, v8
	v_mul_f32_e32 v27, v8, v27
	v_fma_f32 v27, v8, v27, v8
	v_mul_f32_e32 v27, 0xbfcc422a, v27
	v_mul_f32_e32 v27, 0x3fb8aa3b, v27
	v_exp_f32_e32 v27, v27
	s_nop 0
	v_add_f32_e32 v27, 1.0, v27
	s_nop 0
	v_rcp_f32_e32 v28, v27
	s_nop 0
	v_mul_f32_e32 v27, v8, v28
	v_mul_f32_e32 v28, 0x3d372713, v4
	v_mul_f32_e32 v28, v4, v28
	v_fma_f32 v28, v4, v28, v4
	v_mul_f32_e32 v28, 0xbfcc422a, v28
	v_mul_f32_e32 v28, 0x3fb8aa3b, v28
	v_exp_f32_e32 v28, v28
	s_nop 0
	v_add_f32_e32 v28, 1.0, v28
	s_nop 0
	v_rcp_f32_e32 v29, v28
	s_nop 0
	v_mul_f32_e32 v28, v4, v29
	v_mul_f32_e32 v29, 0x3d372713, v9
	v_mul_f32_e32 v29, v9, v29
	v_fma_f32 v29, v9, v29, v9
	v_mul_f32_e32 v29, 0xbfcc422a, v29
	v_mul_f32_e32 v29, 0x3fb8aa3b, v29
	v_exp_f32_e32 v29, v29
	s_nop 0
	v_add_f32_e32 v29, 1.0, v29
	s_nop 0
	v_rcp_f32_e32 v30, v29
	s_nop 0
	v_mul_f32_e32 v29, v9, v30
	v_mul_f32_e32 v30, 0x3d372713, v5
	v_mul_f32_e32 v30, v5, v30
	v_fma_f32 v30, v5, v30, v5
	v_mul_f32_e32 v30, 0xbfcc422a, v30
	v_mul_f32_e32 v30, 0x3fb8aa3b, v30
	v_exp_f32_e32 v30, v30
	v_cvt_pk_bf16_f32 v23, v27, v29
	v_cvt_pk_bf16_f32 v24, v24, v25
	s_nop 0
	v_add_f32_e32 v30, 1.0, v30
	s_mov_b64 s[12:13], 0
	v_rcp_f32_e32 v31, v30
	s_nop 0
	v_mul_f32_e32 v30, v5, v31
	v_cvt_pk_bf16_f32 v25, v28, v30
	global_store_dwordx4 v[20:21], v[22:25], off offset:256
